# tail blocks for rows 16384+ in GEMM phases 5/7/11 (16 m-tiles per XCD); phase 7: first-dispatched WGs (w<32) take 7 tiles, second-dispatched 5; dn_prep late items moved to phase 3 (async counter check
# speedup vs baseline: 1.6708x; 1.0003x over previous
.LBB0_478:
	s_cmp_lg_u32 s8, 0x1f0000
	s_cbranch_scc1 .Ldnl1_a
	s_add_u32 s4, s98, 0x12a8100
	s_addc_u32 s5, s99, 0
	global_load_dword v197, v157, s[4:5] sc1
.Ldnl1_a:
	s_cmp_lg_u32 s8, 0x200000
	s_cbranch_scc1 .Ldnl1_go
	s_waitcnt vmcnt(20)
	v_readfirstlane_b32 s20, v197
	s_cmp_ge_u32 s20, 8
	s_cbranch_scc1 .Ldnl1_acq
	s_add_u32 s4, s98, 0x12a8100
	s_addc_u32 s5, s99, 0
	s_mov_b32 s21, 0
.Ldnl1_spin:
	global_load_dword v197, v157, s[4:5] sc1
	s_waitcnt vmcnt(0)
	v_readfirstlane_b32 s20, v197
	s_cmp_ge_u32 s20, 8
	s_cbranch_scc1 .Ldnl1_acq
	s_sleep 4
	s_add_i32 s21, s21, 1
	s_cmp_lt_u32 s21, 0x2000
	s_cbranch_scc1 .Ldnl1_spin

.LBB0_779:
	s_or_b64 exec, exec, s[0:1]
	v_readlane_b32 s2, v250, 9
	s_and_b32 s2, s2, 7
	s_lshl_b32 s2, s2, 4
	s_movk_i32 s3, 0x80
	s_mov_b32 s4, 16
	v_writelane_b32 v252, s2, 40
	v_writelane_b32 v252, s3, 41
	v_writelane_b32 v252, s4, 44
	s_movk_i32 s3, 0x180
	v_writelane_b32 v252, s3, 45
	s_nop 1
	v_readlane_b32 s0, v252, 42
	v_readlane_b32 s17, v252, 41
	v_readlane_b32 s1, v252, 43
	s_cmp_lt_i32 s0, s17
	s_mov_b32 s16, s0
	s_cselect_b64 s[0:1], -1, 0
	v_writelane_b32 v250, s0, 32
	s_waitcnt lgkmcnt(0)
	s_barrier
	v_writelane_b32 v250, s1, 33
	v_readlane_b32 s0, v252, 13
	v_readlane_b32 s14, v252, 27
	v_readlane_b32 s1, v252, 14
	v_readlane_b32 s15, v252, 28
	s_add_u32 s96, s14, 0x4000000
	s_addc_u32 s97, s15, 0
	v_readlane_b32 s0, v252, 0
	v_readlane_b32 s1, v252, 1
	s_add_u32 s0, s0, 0x1206000
	s_addc_u32 s1, s1, 0
	v_writelane_b32 v250, s0, 3
	s_cmp_ge_i32 s16, s17
	v_readlane_b32 s2, v252, 15
	v_readlane_b32 s3, v252, 16
	v_readlane_b32 s4, v252, 17
	v_readlane_b32 s5, v252, 18
	v_readlane_b32 s6, v252, 19
	v_readlane_b32 s7, v252, 20
	v_readlane_b32 s8, v252, 21
	v_readlane_b32 s9, v252, 22
	v_readlane_b32 s10, v252, 23
	v_readlane_b32 s11, v252, 24
	v_readlane_b32 s12, v252, 25
	v_readlane_b32 s13, v252, 26
	v_writelane_b32 v250, s1, 4
	s_cbranch_scc1 .LBB0_1679
	v_readlane_b32 s0, v252, 41
	s_abs_i32 s1, s0
	v_cvt_f32_u32_e32 v0, s1
	v_writelane_b32 v250, s59, 34
	v_writelane_b32 v250, s58, 35
	s_ashr_i32 s0, s0, 31
	v_rcp_iflag_f32_e32 v0, v0
	v_writelane_b32 v250, s0, 36
	v_readlane_b32 s0, v252, 44
	s_sub_i32 s0, 0, s0
	v_mul_f32_e32 v0, 0x4f7ffffe, v0
	v_cvt_u32_f32_e32 v0, v0
	v_writelane_b32 v250, s0, 37
	v_writelane_b32 v250, s1, 38
	s_sub_i32 s0, 0, s1
	v_readfirstlane_b32 s1, v0
	s_mul_i32 s0, s0, s1
	s_mul_hi_u32 s0, s1, s0
	s_add_i32 s0, s1, s0
	v_writelane_b32 v250, s0, 39
	v_readlane_b32 s0, v252, 42
	v_mov_b32_e32 v65, 0
	s_movk_i32 s33, 0x401f
	s_movk_i32 s88, 0x2010
	v_mov_b32_e32 v171, 0xffffdff0
	s_movk_i32 s89, 0x200f
	s_movk_i32 s92, 0x40a0
	v_mov_b32_e32 v172, 0x1ff0
	s_mov_b32 s93, s0
	v_readlane_b32 s1, v252, 43
	s_branch .LBB0_782

.LBB0_1679:
	s_barrier
	v_readlane_b32 s2, v250, 9
	s_cmpk_gt_u32 s2, 0x9f
	s_cbranch_scc1 .Ltail1_end
	s_lshr_b32 s3, s2, 5
	s_and_b32 s4, s2, 31
	v_readlane_b32 s12, v252, 0
	v_readlane_b32 s13, v252, 1
	s_lshl_b32 s5, s3, 16
	s_add_u32 s8, s12, s5
	s_addc_u32 s9, s13, 0
	s_add_u32 s8, s8, 0x9c4b700
	s_addc_u32 s9, s9, 0
	s_lshl_b32 s5, s4, 16
	v_readlane_b32 s10, v252, 6
	v_readlane_b32 s11, v252, 7
	s_add_u32 s10, s10, s5
	s_addc_u32 s11, s11, 0
	v_and_b32_e32 v66, 31, v218
	v_lshrrev_b32_e32 v77, 6, v218
	v_bfe_u32 v78, v218, 5, 1
	v_lshlrev_b32_e32 v79, 2, v66
	v_mov_b32_e32 v64, v66
	v_lshlrev_b32_e32 v66, 11, v66
	v_lshl_add_u32 v66, v77, 9, v66
	v_lshl_add_u32 v66, v78, 4, v66
	global_load_dwordx4 v[82:85], v66, s[8:9]
	global_load_dwordx4 v[16:19], v66, s[10:11]
	global_load_dwordx4 v[86:89], v66, s[8:9] offset:32
	global_load_dwordx4 v[20:23], v66, s[10:11] offset:32
	global_load_dwordx4 v[90:93], v66, s[8:9] offset:64
	global_load_dwordx4 v[24:27], v66, s[10:11] offset:64
	global_load_dwordx4 v[94:97], v66, s[8:9] offset:96
	global_load_dwordx4 v[28:31], v66, s[10:11] offset:96
	global_load_dwordx4 v[98:101], v66, s[8:9] offset:128
	global_load_dwordx4 v[32:35], v66, s[10:11] offset:128
	global_load_dwordx4 v[102:105], v66, s[8:9] offset:160
	global_load_dwordx4 v[36:39], v66, s[10:11] offset:160
	global_load_dwordx4 v[106:109], v66, s[8:9] offset:192
	global_load_dwordx4 v[40:43], v66, s[10:11] offset:192
	global_load_dwordx4 v[110:113], v66, s[8:9] offset:224
	global_load_dwordx4 v[44:47], v66, s[10:11] offset:224
	global_load_dwordx4 v[114:117], v66, s[8:9] offset:256
	global_load_dwordx4 v[48:51], v66, s[10:11] offset:256
	global_load_dwordx4 v[118:121], v66, s[8:9] offset:288
	global_load_dwordx4 v[52:55], v66, s[10:11] offset:288
	global_load_dwordx4 v[122:125], v66, s[8:9] offset:320
	global_load_dwordx4 v[56:59], v66, s[10:11] offset:320
	global_load_dwordx4 v[126:129], v66, s[8:9] offset:352
	global_load_dwordx4 v[60:63], v66, s[10:11] offset:352
	global_load_dwordx4 v[130:133], v66, s[8:9] offset:384
	global_load_dwordx4 v[150:153], v66, s[10:11] offset:384
	global_load_dwordx4 v[136:139], v66, s[8:9] offset:416
	global_load_dwordx4 v[154:157], v66, s[10:11] offset:416
	global_load_dwordx4 v[140:143], v66, s[8:9] offset:448
	global_load_dwordx4 v[158:161], v66, s[10:11] offset:448
	global_load_dwordx4 v[144:147], v66, s[8:9] offset:480
	global_load_dwordx4 v[162:165], v66, s[10:11] offset:480
	v_readlane_b32 s12, v252, 27
	v_readlane_b32 s13, v252, 28
	s_cmp_eq_u32 s3, 0
	s_cbranch_scc1 .Ltail1_p
	s_add_i32 s5, s3, -1
	s_lshl_b32 s5, s5, 17
	s_add_u32 s14, s62, s5
	s_addc_u32 s15, s63, 0
	s_add_u32 s16, s96, s5
	s_addc_u32 s17, s97, 0
	s_branch .Ltail1_q

.Ltail1_q:
	s_lshl_b32 s5, s4, 7
	s_add_u32 s14, s14, s5
	s_addc_u32 s15, s15, 0
	s_add_u32 s16, s16, s5
	s_addc_u32 s17, s17, 0
	v_lshl_add_u32 v67, v77, 15, v79
	v_lshl_add_u32 v67, v78, 14, v67
	v_add_u32_e32 v68, 0x1000, v67
	v_add_u32_e32 v69, 0x2000, v67
	v_add_u32_e32 v70, 0x3000, v67
	global_load_dword v71, v67, s[14:15] nt
	global_load_dword v72, v68, s[14:15] nt
	global_load_dword v73, v69, s[14:15] nt
	global_load_dword v74, v70, s[14:15] nt
	v_and_b32_e32 v75, 63, v218
	v_lshlrev_b32_e32 v75, 4, v75
	v_lshl_add_u32 v76, v77, 10, v75
	v_lshl_add_u32 v75, v77, 12, v75
	s_waitcnt vmcnt(34)
	v_mfma_f32_32x32x16_bf16 v[0:15], v[82:85], v[16:19], 0
	s_waitcnt vmcnt(32)
	v_mfma_f32_32x32x16_bf16 v[0:15], v[86:89], v[20:23], v[0:15]
	s_waitcnt vmcnt(30)
	v_mfma_f32_32x32x16_bf16 v[0:15], v[90:93], v[24:27], v[0:15]
	s_waitcnt vmcnt(28)
	v_mfma_f32_32x32x16_bf16 v[0:15], v[94:97], v[28:31], v[0:15]
	s_waitcnt vmcnt(26)
	v_mfma_f32_32x32x16_bf16 v[0:15], v[98:101], v[32:35], v[0:15]
	s_waitcnt vmcnt(24)
	v_mfma_f32_32x32x16_bf16 v[0:15], v[102:105], v[36:39], v[0:15]
	s_waitcnt vmcnt(22)
	v_mfma_f32_32x32x16_bf16 v[0:15], v[106:109], v[40:43], v[0:15]
	s_waitcnt vmcnt(20)
	v_mfma_f32_32x32x16_bf16 v[0:15], v[110:113], v[44:47], v[0:15]
	s_waitcnt vmcnt(18)
	v_mfma_f32_32x32x16_bf16 v[0:15], v[114:117], v[48:51], v[0:15]
	s_waitcnt vmcnt(16)
	v_mfma_f32_32x32x16_bf16 v[0:15], v[118:121], v[52:55], v[0:15]
	s_waitcnt vmcnt(14)
	v_mfma_f32_32x32x16_bf16 v[0:15], v[122:125], v[56:59], v[0:15]
	s_waitcnt vmcnt(12)
	v_mfma_f32_32x32x16_bf16 v[0:15], v[126:129], v[60:63], v[0:15]
	s_waitcnt vmcnt(10)
	v_mfma_f32_32x32x16_bf16 v[0:15], v[130:133], v[150:153], v[0:15]
	s_waitcnt vmcnt(8)
	v_mfma_f32_32x32x16_bf16 v[0:15], v[136:139], v[154:157], v[0:15]
	s_waitcnt vmcnt(6)
	v_mfma_f32_32x32x16_bf16 v[0:15], v[140:143], v[158:161], v[0:15]
	s_waitcnt vmcnt(4)
	v_mfma_f32_32x32x16_bf16 v[0:15], v[144:147], v[162:165], v[0:15]
	s_nop 15
	s_nop 15
	ds_write_b128 v75, v[0:3]
	ds_write_b128 v75, v[4:7] offset:1024
	ds_write_b128 v75, v[8:11] offset:2048
	ds_write_b128 v75, v[12:15] offset:3072
	s_waitcnt lgkmcnt(0)
	s_barrier
	ds_read_b128 v[16:19], v76
	ds_read_b128 v[20:23], v76 offset:4096
	ds_read_b128 v[24:27], v76 offset:8192
	ds_read_b128 v[28:31], v76 offset:12288
	s_waitcnt lgkmcnt(0)
	v_pk_add_f32 v[16:17], v[16:17], v[20:21]
	v_pk_add_f32 v[18:19], v[18:19], v[22:23]
	v_pk_add_f32 v[24:25], v[24:25], v[28:29]
	v_pk_add_f32 v[26:27], v[26:27], v[30:31]
	v_pk_add_f32 v[16:17], v[16:17], v[24:25]
	v_pk_add_f32 v[18:19], v[18:19], v[26:27]
	s_waitcnt vmcnt(0)
	v_add_f32_e32 v71, v71, v16
	global_store_dword v67, v71, s[16:17]
	v_add_f32_e32 v72, v72, v17
	global_store_dword v68, v72, s[16:17]
	v_add_f32_e32 v73, v73, v18
	global_store_dword v69, v73, s[16:17]
	v_add_f32_e32 v74, v74, v19
	global_store_dword v70, v74, s[16:17]
.Ltail1_end:
	s_waitcnt vmcnt(0)
	v_readlane_b32 s4, v252, 31
	v_readlane_b32 s5, v252, 32
	s_barrier
	s_mov_b64 s[2:3], exec
	v_readlane_b32 s0, v252, 33
	v_readlane_b32 s1, v252, 34
	s_and_b64 s[0:1], s[2:3], s[0:1]
	s_mov_b64 exec, s[0:1]
	s_cbranch_execz .LBB0_1691
	v_mov_b32_e32 v0, 0x12400
	ds_read_b32 v0, v0
	s_mov_b64 s[0:1], -1
	s_waitcnt lgkmcnt(0)
	v_cmp_eq_u32_e32 vcc, 0, v0
	s_cbranch_vccz .LBB0_1690
	s_waitcnt vmcnt(3)
	v_mbcnt_hi_u32_b32 v5, -1, v219
	v_and_b32_e32 v0, 64, v5
	s_waitcnt vmcnt(2)
	v_add_u32_e32 v6, 64, v0
	v_xor_b32_e32 v0, 32, v5
	v_cmp_lt_i32_e32 vcc, v0, v6
	v_xor_b32_e32 v1, 16, v5
	v_xor_b32_e32 v2, 8, v5
	v_cndmask_b32_e32 v0, v5, v0, vcc
	v_cmp_lt_i32_e32 vcc, v1, v6
	v_xor_b32_e32 v3, 4, v5
	v_xor_b32_e32 v4, 2, v5
	v_cndmask_b32_e32 v1, v5, v1, vcc
	v_cmp_lt_i32_e32 vcc, v2, v6
	v_xor_b32_e32 v7, 1, v5
	v_lshlrev_b32_e32 v0, 2, v0
	v_cndmask_b32_e32 v2, v5, v2, vcc
	v_cmp_lt_i32_e32 vcc, v3, v6
	v_lshlrev_b32_e32 v1, 2, v1
	v_lshlrev_b32_e32 v2, 2, v2
	v_cndmask_b32_e32 v3, v5, v3, vcc
	v_cmp_lt_i32_e32 vcc, v4, v6
	v_lshlrev_b32_e32 v3, 2, v3
	s_mov_b64 s[4:5], 0
	v_cndmask_b32_e32 v4, v5, v4, vcc
	v_cmp_lt_i32_e32 vcc, v7, v6
	v_lshlrev_b32_e32 v4, 2, v4
	v_mov_b32_e32 v6, 0x100000
	v_cndmask_b32_e32 v5, v5, v7, vcc
	v_lshlrev_b32_e32 v5, 2, v5
	s_branch .LBB0_1683

.LBB0_1851:
	s_or_b64 exec, exec, s[0:1]
	v_readlane_b32 s0, v252, 42
	s_movk_i32 s4, 0x180
	s_movk_i32 s5, 0xe0
	s_cmp_lt_u32 s0, 32
	s_cselect_b32 s1, 0, 0xc0
	s_cselect_b32 s4, s5, s4
	s_add_i32 s1, s0, s1
	v_writelane_b32 v250, s1, 42
	v_writelane_b32 v250, s4, 43
	s_nop 1
	v_readlane_b32 s0, v250, 42
	v_readlane_b32 s1, v250, 43
	s_cmp_ge_i32 s0, s1
	s_waitcnt lgkmcnt(0)
	s_barrier
	s_cbranch_scc1 .LBB0_1862
	v_readlane_b32 s0, v252, 41
	s_abs_i32 s11, s0
	s_waitcnt vmcnt(3)
	v_cvt_f32_u32_e32 v0, s11
	s_ashr_i32 s10, s0, 31
	s_sub_i32 s0, 0, s11
	v_mov_b32_e32 v65, 0
	v_rcp_iflag_f32_e32 v0, v0
	s_mov_b32 s14, 0x10000
	s_mov_b32 s15, 0x20000
	s_mov_b32 s16, 0x30000
	v_mul_f32_e32 v0, 0x4f7ffffe, v0
	v_cvt_u32_f32_e32 v0, v0
	s_movk_i32 s17, 0x1800
	s_movk_i32 s18, 0x7fff
	s_movk_i32 s19, 0x4180
	v_readfirstlane_b32 s1, v0
	s_mul_i32 s0, s0, s1
	s_mul_hi_u32 s0, s1, s0
	s_add_i32 s12, s1, s0
	v_readlane_b32 s0, v252, 44
	s_sub_i32 s13, 0, s0
	v_readlane_b32 s0, v250, 42
	s_mov_b64 s[2:3], 0x7c0b800
	s_mov_b32 s20, 0x5040100
	s_mov_b32 s21, 0x7c0b000
	v_mov_b32_e32 v81, 1
	s_mov_b32 s22, s0
	v_readlane_b32 s1, v252, 43
	s_branch .LBB0_1854
.LBB0_1853:
	s_add_i32 s22, s22, 32
	v_readlane_b32 s0, v250, 43
	s_cmp_lt_i32 s22, s0
	s_cbranch_scc0 .LBB0_1862

.LBB0_1862:
	s_barrier
	v_readlane_b32 s0, v250, 9
	s_cmpk_gt_u32 s0, 0x1df
	s_cbranch_scc1 .Ltail2_end
	s_mul_i32 s1, s0, 0x2ab
	s_lshr_b32 s1, s1, 16
	s_mul_i32 s5, s1, 0x60
	s_sub_i32 s4, s0, s5
	v_readlane_b32 s18, v252, 0
	v_readlane_b32 s19, v252, 1
	s_lshl_b32 s5, s1, 16
	s_add_u32 s10, s18, s5
	s_addc_u32 s11, s19, 0
	s_add_u32 s10, s10, 0xdd8b700
	s_addc_u32 s11, s11, 0
	s_lshl_b32 s5, s4, 16
	v_readlane_b32 s12, v250, 13
	v_readlane_b32 s13, v250, 14
	s_add_u32 s12, s12, s5
	s_addc_u32 s13, s13, 0
	v_and_b32_e32 v66, 31, v218
	v_lshrrev_b32_e32 v77, 6, v218
	v_bfe_u32 v78, v218, 5, 1
	v_lshlrev_b32_e32 v79, 2, v66
	v_mov_b32_e32 v64, v66
	v_lshlrev_b32_e32 v66, 11, v66
	v_lshl_add_u32 v66, v77, 9, v66
	v_lshl_add_u32 v66, v78, 4, v66
	global_load_dwordx4 v[82:85], v66, s[10:11]
	global_load_dwordx4 v[16:19], v66, s[12:13]
	global_load_dwordx4 v[86:89], v66, s[10:11] offset:32
	global_load_dwordx4 v[20:23], v66, s[12:13] offset:32
	global_load_dwordx4 v[90:93], v66, s[10:11] offset:64
	global_load_dwordx4 v[24:27], v66, s[12:13] offset:64
	global_load_dwordx4 v[94:97], v66, s[10:11] offset:96
	global_load_dwordx4 v[28:31], v66, s[12:13] offset:96
	global_load_dwordx4 v[98:101], v66, s[10:11] offset:128
	global_load_dwordx4 v[32:35], v66, s[12:13] offset:128
	global_load_dwordx4 v[102:105], v66, s[10:11] offset:160
	global_load_dwordx4 v[36:39], v66, s[12:13] offset:160
	global_load_dwordx4 v[106:109], v66, s[10:11] offset:192
	global_load_dwordx4 v[40:43], v66, s[12:13] offset:192
	global_load_dwordx4 v[110:113], v66, s[10:11] offset:224
	global_load_dwordx4 v[44:47], v66, s[12:13] offset:224
	global_load_dwordx4 v[114:117], v66, s[10:11] offset:256
	global_load_dwordx4 v[48:51], v66, s[12:13] offset:256
	global_load_dwordx4 v[118:121], v66, s[10:11] offset:288
	global_load_dwordx4 v[52:55], v66, s[12:13] offset:288
	global_load_dwordx4 v[122:125], v66, s[10:11] offset:320
	global_load_dwordx4 v[56:59], v66, s[12:13] offset:320
	global_load_dwordx4 v[126:129], v66, s[10:11] offset:352
	global_load_dwordx4 v[60:63], v66, s[12:13] offset:352
	global_load_dwordx4 v[130:133], v66, s[10:11] offset:384
	global_load_dwordx4 v[150:153], v66, s[12:13] offset:384
	global_load_dwordx4 v[136:139], v66, s[10:11] offset:416
	global_load_dwordx4 v[154:157], v66, s[12:13] offset:416
	global_load_dwordx4 v[140:143], v66, s[10:11] offset:448
	global_load_dwordx4 v[158:161], v66, s[12:13] offset:448
	global_load_dwordx4 v[144:147], v66, s[10:11] offset:480
	global_load_dwordx4 v[162:165], v66, s[12:13] offset:480
	s_mul_i32 s5, s1, 0x30000
	s_add_u32 s14, s18, s5
	s_addc_u32 s15, s19, 0
	s_lshl_b32 s5, s4, 6
	s_add_i32 s5, s5, 0x72ab700
	s_add_u32 s14, s14, s5
	s_addc_u32 s15, s15, 0
	s_lshl_b32 s5, s4, 5
	s_sub_i32 s5, s5, 0x400
	s_mul_i32 s5, s5, 0x8300
	s_add_u32 s16, s18, s5
	s_addc_u32 s17, s19, 0
	s_lshl_b32 s5, s1, 6
	s_add_i32 s5, s5, 0x9cd3800
	s_add_u32 s16, s16, s5
	s_addc_u32 s17, s17, 0
	v_lshlrev_b32_e32 v67, 3, v77
	v_lshl_add_u32 v67, v78, 2, v67
	v_lshlrev_b32_e32 v71, 1, v67
	v_mul_u32_u24_e32 v67, 0x1800, v67
	v_lshl_add_u32 v67, v64, 1, v67
	v_add_u32_e32 v68, 0x1800, v67
	v_add_u32_e32 v69, 0x3000, v67
	v_add_u32_e32 v70, 0x4800, v67
	v_mul_u32_u24_e32 v72, 0x8300, v64
	v_add_u32_e32 v71, v71, v72
	v_and_b32_e32 v75, 63, v218
	v_lshlrev_b32_e32 v75, 4, v75
	v_lshl_add_u32 v76, v77, 10, v75
	v_lshl_add_u32 v75, v77, 12, v75
	s_waitcnt vmcnt(30)
	v_mfma_f32_32x32x16_bf16 v[0:15], v[82:85], v[16:19], 0
	s_waitcnt vmcnt(28)
	v_mfma_f32_32x32x16_bf16 v[0:15], v[86:89], v[20:23], v[0:15]
	s_waitcnt vmcnt(26)
	v_mfma_f32_32x32x16_bf16 v[0:15], v[90:93], v[24:27], v[0:15]
	s_waitcnt vmcnt(24)
	v_mfma_f32_32x32x16_bf16 v[0:15], v[94:97], v[28:31], v[0:15]
	s_waitcnt vmcnt(22)
	v_mfma_f32_32x32x16_bf16 v[0:15], v[98:101], v[32:35], v[0:15]
	s_waitcnt vmcnt(20)
	v_mfma_f32_32x32x16_bf16 v[0:15], v[102:105], v[36:39], v[0:15]
	s_waitcnt vmcnt(18)
	v_mfma_f32_32x32x16_bf16 v[0:15], v[106:109], v[40:43], v[0:15]
	s_waitcnt vmcnt(16)
	v_mfma_f32_32x32x16_bf16 v[0:15], v[110:113], v[44:47], v[0:15]
	s_waitcnt vmcnt(14)
	v_mfma_f32_32x32x16_bf16 v[0:15], v[114:117], v[48:51], v[0:15]
	s_waitcnt vmcnt(12)
	v_mfma_f32_32x32x16_bf16 v[0:15], v[118:121], v[52:55], v[0:15]
	s_waitcnt vmcnt(10)
	v_mfma_f32_32x32x16_bf16 v[0:15], v[122:125], v[56:59], v[0:15]
	s_waitcnt vmcnt(8)
	v_mfma_f32_32x32x16_bf16 v[0:15], v[126:129], v[60:63], v[0:15]
	s_waitcnt vmcnt(6)
	v_mfma_f32_32x32x16_bf16 v[0:15], v[130:133], v[150:153], v[0:15]
	s_waitcnt vmcnt(4)
	v_mfma_f32_32x32x16_bf16 v[0:15], v[136:139], v[154:157], v[0:15]
	s_waitcnt vmcnt(2)
	v_mfma_f32_32x32x16_bf16 v[0:15], v[140:143], v[158:161], v[0:15]
	s_waitcnt vmcnt(0)
	v_mfma_f32_32x32x16_bf16 v[0:15], v[144:147], v[162:165], v[0:15]
	s_nop 15
	s_nop 15
	ds_write_b128 v75, v[0:3]
	ds_write_b128 v75, v[4:7] offset:1024
	ds_write_b128 v75, v[8:11] offset:2048
	ds_write_b128 v75, v[12:15] offset:3072
	s_waitcnt lgkmcnt(0)
	s_barrier
	ds_read_b128 v[16:19], v76
	ds_read_b128 v[20:23], v76 offset:4096
	ds_read_b128 v[24:27], v76 offset:8192
	ds_read_b128 v[28:31], v76 offset:12288
	s_waitcnt lgkmcnt(0)
	v_pk_add_f32 v[16:17], v[16:17], v[20:21]
	v_pk_add_f32 v[18:19], v[18:19], v[22:23]
	v_pk_add_f32 v[24:25], v[24:25], v[28:29]
	v_pk_add_f32 v[26:27], v[26:27], v[30:31]
	v_pk_add_f32 v[16:17], v[16:17], v[24:25]
	v_pk_add_f32 v[18:19], v[18:19], v[26:27]
	v_cvt_pk_bf16_f32 v20, v16, v17
	v_cvt_pk_bf16_f32 v21, v18, v19
	global_store_short v67, v20, s[14:15]
	global_store_short_d16_hi v68, v20, s[14:15]
	global_store_short v69, v21, s[14:15]
	global_store_short_d16_hi v70, v21, s[14:15]
	s_sub_i32 s5, s4, 32
	s_cmp_lt_u32 s5, 32
	s_cbranch_scc0 .Ltail2_end
	global_store_dwordx2 v71, v[20:21], s[16:17]

.LBB0_3031:
	s_barrier
	v_readlane_b32 s2, v250, 9
	s_cmpk_gt_u32 s2, 0x9f
	s_cbranch_scc1 .Ltail3_end
	s_lshr_b32 s3, s2, 5
	s_and_b32 s4, s2, 31
	v_readlane_b32 s12, v252, 0
	v_readlane_b32 s13, v252, 1
	s_lshl_b32 s5, s3, 16
	s_add_u32 s8, s12, s5
	s_addc_u32 s9, s13, 0
	s_add_u32 s8, s8, 0x9c4b700
	s_addc_u32 s9, s9, 0
	s_lshl_b32 s5, s4, 16
	v_readlane_b32 s10, v250, 15
	v_readlane_b32 s11, v250, 16
	s_add_u32 s10, s10, s5
	s_addc_u32 s11, s11, 0
	v_and_b32_e32 v66, 31, v218
	v_lshrrev_b32_e32 v77, 6, v218
	v_bfe_u32 v78, v218, 5, 1
	v_lshlrev_b32_e32 v79, 2, v66
	v_mov_b32_e32 v64, v66
	v_lshlrev_b32_e32 v66, 11, v66
	v_lshl_add_u32 v66, v77, 9, v66
	v_lshl_add_u32 v66, v78, 4, v66
	global_load_dwordx4 v[82:85], v66, s[8:9]
	global_load_dwordx4 v[16:19], v66, s[10:11]
	global_load_dwordx4 v[86:89], v66, s[8:9] offset:32
	global_load_dwordx4 v[20:23], v66, s[10:11] offset:32
	global_load_dwordx4 v[90:93], v66, s[8:9] offset:64
	global_load_dwordx4 v[24:27], v66, s[10:11] offset:64
	global_load_dwordx4 v[94:97], v66, s[8:9] offset:96
	global_load_dwordx4 v[28:31], v66, s[10:11] offset:96
	global_load_dwordx4 v[98:101], v66, s[8:9] offset:128
	global_load_dwordx4 v[32:35], v66, s[10:11] offset:128
	global_load_dwordx4 v[102:105], v66, s[8:9] offset:160
	global_load_dwordx4 v[36:39], v66, s[10:11] offset:160
	global_load_dwordx4 v[106:109], v66, s[8:9] offset:192
	global_load_dwordx4 v[40:43], v66, s[10:11] offset:192
	global_load_dwordx4 v[110:113], v66, s[8:9] offset:224
	global_load_dwordx4 v[44:47], v66, s[10:11] offset:224
	global_load_dwordx4 v[114:117], v66, s[8:9] offset:256
	global_load_dwordx4 v[48:51], v66, s[10:11] offset:256
	global_load_dwordx4 v[118:121], v66, s[8:9] offset:288
	global_load_dwordx4 v[52:55], v66, s[10:11] offset:288
	global_load_dwordx4 v[122:125], v66, s[8:9] offset:320
	global_load_dwordx4 v[56:59], v66, s[10:11] offset:320
	global_load_dwordx4 v[126:129], v66, s[8:9] offset:352
	global_load_dwordx4 v[60:63], v66, s[10:11] offset:352
	global_load_dwordx4 v[130:133], v66, s[8:9] offset:384
	global_load_dwordx4 v[150:153], v66, s[10:11] offset:384
	global_load_dwordx4 v[136:139], v66, s[8:9] offset:416
	global_load_dwordx4 v[154:157], v66, s[10:11] offset:416
	global_load_dwordx4 v[140:143], v66, s[8:9] offset:448
	global_load_dwordx4 v[158:161], v66, s[10:11] offset:448
	global_load_dwordx4 v[144:147], v66, s[8:9] offset:480
	global_load_dwordx4 v[162:165], v66, s[10:11] offset:480
	v_readlane_b32 s12, v252, 27
	v_readlane_b32 s13, v252, 28
	s_cmp_eq_u32 s3, 0
	s_cbranch_scc1 .Ltail3_p
	s_add_i32 s5, s3, -1
	s_lshl_b32 s5, s5, 17
	s_add_u32 s14, s62, s5
	s_addc_u32 s15, s63, 0
	s_add_u32 s16, s96, s5
	s_addc_u32 s17, s97, 0
	s_branch .Ltail3_q

.Ltail3_q:
	s_lshl_b32 s5, s4, 7
	s_add_u32 s14, s14, s5
	s_addc_u32 s15, s15, 0
	s_add_u32 s16, s16, s5
	s_addc_u32 s17, s17, 0
	s_mov_b64 s[14:15], s[16:17]
	v_lshl_add_u32 v67, v77, 15, v79
	v_lshl_add_u32 v67, v78, 14, v67
	v_add_u32_e32 v68, 0x1000, v67
	v_add_u32_e32 v69, 0x2000, v67
	v_add_u32_e32 v70, 0x3000, v67
	global_load_dword v71, v67, s[14:15] nt
	global_load_dword v72, v68, s[14:15] nt
	global_load_dword v73, v69, s[14:15] nt
	global_load_dword v74, v70, s[14:15] nt
	v_and_b32_e32 v75, 63, v218
	v_lshlrev_b32_e32 v75, 4, v75
	v_lshl_add_u32 v76, v77, 10, v75
	v_lshl_add_u32 v75, v77, 12, v75
	s_waitcnt vmcnt(34)
	v_mfma_f32_32x32x16_bf16 v[0:15], v[82:85], v[16:19], 0
	s_waitcnt vmcnt(32)
	v_mfma_f32_32x32x16_bf16 v[0:15], v[86:89], v[20:23], v[0:15]
	s_waitcnt vmcnt(30)
	v_mfma_f32_32x32x16_bf16 v[0:15], v[90:93], v[24:27], v[0:15]
	s_waitcnt vmcnt(28)
	v_mfma_f32_32x32x16_bf16 v[0:15], v[94:97], v[28:31], v[0:15]
	s_waitcnt vmcnt(26)
	v_mfma_f32_32x32x16_bf16 v[0:15], v[98:101], v[32:35], v[0:15]
	s_waitcnt vmcnt(24)
	v_mfma_f32_32x32x16_bf16 v[0:15], v[102:105], v[36:39], v[0:15]
	s_waitcnt vmcnt(22)
	v_mfma_f32_32x32x16_bf16 v[0:15], v[106:109], v[40:43], v[0:15]
	s_waitcnt vmcnt(20)
	v_mfma_f32_32x32x16_bf16 v[0:15], v[110:113], v[44:47], v[0:15]
	s_waitcnt vmcnt(18)
	v_mfma_f32_32x32x16_bf16 v[0:15], v[114:117], v[48:51], v[0:15]
	s_waitcnt vmcnt(16)
	v_mfma_f32_32x32x16_bf16 v[0:15], v[118:121], v[52:55], v[0:15]
	s_waitcnt vmcnt(14)
	v_mfma_f32_32x32x16_bf16 v[0:15], v[122:125], v[56:59], v[0:15]
	s_waitcnt vmcnt(12)
	v_mfma_f32_32x32x16_bf16 v[0:15], v[126:129], v[60:63], v[0:15]
	s_waitcnt vmcnt(10)
	v_mfma_f32_32x32x16_bf16 v[0:15], v[130:133], v[150:153], v[0:15]
	s_waitcnt vmcnt(8)
	v_mfma_f32_32x32x16_bf16 v[0:15], v[136:139], v[154:157], v[0:15]
	s_waitcnt vmcnt(6)
	v_mfma_f32_32x32x16_bf16 v[0:15], v[140:143], v[158:161], v[0:15]
	s_waitcnt vmcnt(4)
	v_mfma_f32_32x32x16_bf16 v[0:15], v[144:147], v[162:165], v[0:15]
	s_nop 15
	s_nop 15
	ds_write_b128 v75, v[0:3]
	ds_write_b128 v75, v[4:7] offset:1024
	ds_write_b128 v75, v[8:11] offset:2048
	ds_write_b128 v75, v[12:15] offset:3072
	s_waitcnt lgkmcnt(0)
	s_barrier
	ds_read_b128 v[16:19], v76
	ds_read_b128 v[20:23], v76 offset:4096
	ds_read_b128 v[24:27], v76 offset:8192
	ds_read_b128 v[28:31], v76 offset:12288
	s_waitcnt lgkmcnt(0)
	v_pk_add_f32 v[16:17], v[16:17], v[20:21]
	v_pk_add_f32 v[18:19], v[18:19], v[22:23]
	v_pk_add_f32 v[24:25], v[24:25], v[28:29]
	v_pk_add_f32 v[26:27], v[26:27], v[30:31]
	v_pk_add_f32 v[16:17], v[16:17], v[24:25]
	v_pk_add_f32 v[18:19], v[18:19], v[26:27]
	s_waitcnt vmcnt(0)
	v_add_f32_e32 v71, v71, v16
	global_store_dword v67, v71, s[16:17]
	v_add_f32_e32 v72, v72, v17
	global_store_dword v68, v72, s[16:17]
	v_add_f32_e32 v73, v73, v18
	global_store_dword v69, v73, s[16:17]
	v_add_f32_e32 v74, v74, v19
	global_store_dword v70, v74, s[16:17]
